# attention phase rewritten: 64 q rows per wave (two 32-row blocks share each K/V fragment read from LDS), 512-row items, non-pipelined tile loop; same bf16 MFMA/f32 softmax math and LDS layouts
# speedup vs baseline: 1.0131x; 1.0082x over previous
; __device__ __forceinline__ int v_st(int k, int c) { const int kk = (k & ~0xC) | ((k & 4) << 1) | ((k & 8) >> 1); return ((kk >> 3) * 4 + (c >> 5)) * 512 + ((kk & 7) * 32 + (c & 31)) * 2; }
; __device__ __forceinline__ int v_rd_base(int lane) { return ((lane & 3) << 3) | (((lane >> 2) & 3) << 6) | (((lane >> 4) & 1) << 5) | (((lane >> 5) & 1) << 8); }
; __device__ __forceinline__ void attn_body(const bf16_t* __restrict__ Qb, const bf16_t* __restrict__ KVh, const bf16_t* __restrict__ KR, const float* __restrict__ ropeq,
;                                           bf16_t* __restrict__ Ob, int seq, char* lds, const int tid) {
;     ...
;     const int sr = tid >> 4, c16 = tid & 15;
;     const bool isK = c16 < 8;
;     const int kst0 = KSWZ(sr, c16 * 16), kst1 = KSWZ(32 + sr, c16 * 16), vst0 = v_st(sr, (c16 & 7) * 8), vst1 = v_st(32 + sr, (c16 & 7) * 8);
;     const int rkey = (tid & 255) >> 2, rch = tid & 3; const int rst = KSWZ(rkey, 128 + rch * 16); const bool rwr = tid < 256;
;     const int vb0 = (int)(uintptr_t)V_lds + v_rd_base(lane);
; __device__ __forceinline__ void phase_attn(const Ctx& C, PP p, char* lds_generic) {
;     unsigned char* ws = p->ws;
;     const bf16_t* Q = (const bf16_t*)(ws + WS_BIG); const bf16_t* KV = (const bf16_t*)(ws + WS_KV); const bf16_t* KR = (const bf16_t*)(ws + WS_KR);
;     const float* rope = (const float*)(ws + WS_ROPE); bf16_t* O = (bf16_t*)(ws + WS_HAB);
;     for (int it = C.vcu; it < 2048; it += C.G) {
;         const int qb = it & 15, h = (it >> 4) & 15, b = it >> 8; const size_t t0 = (size_t)b * SEQ, q0 = t0 + qb * 256;
;         __syncthreads();
;         att::attn_body(Q + q0 * NQ + h * 96, KV + t0 * NKV + h * 128, KR + t0 * 32, rope + q0 * 32, O + q0 * DM + h * 64, SEQ, lds_generic, C.tid);
.LBB0_39:
	s_andn2_b64 vcc, exec, s[0:1]
	s_cbranch_vccnz .LBB0_79
	s_cmpk_gt_i32 s89, 0x3ff
	s_cbranch_scc1 .LBB0_78
	v_and_b32_e32 v2, 0x3fffffc0, v140
	s_add_i32 s0, 0, 0x18000
	v_lshl_add_u32 v139, v2, 2, s0
	v_ashrrev_i32_e32 v3, 1, v140
	s_movk_i32 s0, 0xffe0
	v_bfi_b32 v4, s0, v3, v140
	s_movk_i32 s0, 0xc00
	v_mad_i64_i32 v[130:131], s[0:1], v4, s0, 0
	v_ashrrev_i32_e32 v5, 31, v4
	v_readlane_b32 s0, v253, 43
	v_lshlrev_b64 v[4:5], 7, v[4:5]
	v_readlane_b32 s1, v253, 44
	v_and_b32_e32 v64, 32, v211
	v_and_b32_e32 v2, 0xffffffe0, v3
	v_lshl_add_u64 v[4:5], s[0:1], 0, v[4:5]
	v_lshl_add_u64 v[132:133], v[4:5], 0, v[64:65]
	v_ashrrev_i32_e32 v4, 4, v140
	v_and_b32_e32 v3, 15, v140
	v_lshlrev_b32_e32 v5, 8, v4
	v_lshlrev_b32_e32 v7, 4, v3
	v_and_b32_e32 v9, 0x70, v140
	v_add_u32_e32 v8, 32, v4
	v_bitop3_b32 v141, v7, v5, v9 bitop3:0xde
	v_lshlrev_b32_e32 v5, 8, v8
	v_bitop3_b32 v182, v5, v7, v9 bitop3:0xf6
	v_and_b32_e32 v5, 0xfffff0, v4
	v_lshlrev_b32_e32 v9, 1, v4
	v_and_or_b32 v5, v9, 8, v5
	v_lshrrev_b32_e32 v9, 1, v4
	v_lshrrev_b32_e32 v5, 1, v5
	v_bfe_u32 v10, v140, 2, 1
	v_and_b32_e32 v11, 3, v4
	v_or_b32_e32 v5, v5, v10
	v_and_or_b32 v9, v9, 4, v11
	v_lshlrev_b32_e32 v11, 4, v140
	v_lshlrev_b32_e32 v5, 9, v5
	v_lshlrev_b32_e32 v9, 6, v9
	v_and_b32_e32 v12, 48, v11
	v_or3_b32 v183, v5, v9, v12
	v_and_b32_e32 v5, 0xfffff0, v8
	v_lshlrev_b32_e32 v13, 1, v8
	v_and_or_b32 v5, v13, 8, v5
	v_lshrrev_b32_e32 v5, 1, v5
	v_or_b32_e32 v5, v5, v10
	v_lshlrev_b32_e32 v5, 9, v5
	v_or3_b32 v184, v5, v9, v12
	v_bfe_u32 v12, v140, 2, 6
	v_and_b32_e32 v13, 3, v140
	v_mov_b32_e32 v9, 0x80
	v_lshlrev_b32_e32 v10, 2, v140
	v_lshlrev_b32_e32 v5, 8, v12
	v_lshl_or_b32 v9, v13, 4, v9
	v_and_b32_e32 v10, 0x70, v10
	v_bitop3_b32 v14, v9, v5, v10 bitop3:0xde
	v_lshlrev_b32_e32 v9, 4, v211
	v_lshlrev_b32_e32 v5, 3, v211
	v_and_b32_e32 v9, 0xc0, v9
	v_lshlrev_b32_e32 v10, 1, v211
	v_lshrrev_b32_e32 v1, 5, v211
	v_and_or_b32 v9, v5, 24, v9
	v_and_b32_e32 v10, 32, v10
	v_and_b32_e32 v5, 0x100, v5
	v_and_b32_e32 v0, 31, v140
	v_or3_b32 v15, v9, v10, v5
	v_ashrrev_i32_e32 v5, 31, v4
	v_ashrrev_i32_e32 v9, 31, v8
	v_lshlrev_b32_e32 v187, 4, v1
	v_lshlrev_b64 v[134:135], 12, v[4:5]
	v_lshlrev_b64 v[142:143], 12, v[8:9]
	v_lshlrev_b32_e32 v5, 8, v0
	v_and_b32_e32 v8, 0x70, v11
	v_or_b32_e32 v9, 32, v187
	v_bitop3_b32 v189, v9, v5, v8 bitop3:0xde
	v_or_b32_e32 v9, 64, v187
	v_bitop3_b32 v212, v9, v5, v8 bitop3:0xde
	v_or_b32_e32 v9, 0x60, v187
	s_cmp_lg_u32 0, -1
	v_lshlrev_b32_e32 v4, 3, v13
	v_bitop3_b32 v213, v9, v5, v8 bitop3:0xde
	v_or_b32_e32 v9, 0x80, v187
	s_mov_b64 s[4:5], 0x40000
	s_cselect_b32 s6, 0, 0
	v_lshl_or_b32 v4, v12, 5, v4
	v_bitop3_b32 v214, v9, v5, v8 bitop3:0xde
	v_or_b32_e32 v9, 0xa0, v187
	v_lshl_add_u64 v[144:145], v[134:135], 0, s[4:5]
	s_mov_b64 s[4:5], 0x60000
	s_add_i32 s7, 0, 0xc000
	v_lshlrev_b32_e32 v6, 3, v1
	v_cmp_lt_u32_e64 s[0:1], 7, v3
	s_movk_i32 s2, 0x100
	v_add_u32_e32 v185, s6, v15
	v_lshlrev_b32_e32 v10, 3, v3
	v_bitop3_b32 v188, v187, v5, v8 bitop3:0xde
	v_bitop3_b32 v215, v9, v5, v8 bitop3:0xde
	v_lshl_add_u64 v[146:147], v[134:135], 0, s[4:5]
	s_mov_b64 s[4:5], 0xa0000
	v_mov_b32_e32 v5, s7
	v_cmp_gt_u32_e32 vcc, 8, v3
	s_add_i32 s6, s6, 0x8000
	v_ashrrev_i32_e32 v3, 31, v2
	v_lshlrev_b32_e32 v154, 13, v1
	v_lshlrev_b32_e32 v1, 1, v4
	v_cmp_gt_i32_e64 s[2:3], s2, v140
	v_add_u32_e32 v186, 0, v14
	v_lshl_add_u64 v[148:149], v[134:135], 0, s[56:57]
	v_lshl_add_u64 v[150:151], v[134:135], 0, s[4:5]
	v_cmp_gt_u32_e64 s[4:5], 32, v211
	v_lshl_add_u32 v216, v0, 2, v139
	v_cndmask_b32_e32 v217, 0, v5, vcc
	v_cndmask_b32_e32 v218, v183, v141, vcc
	v_cndmask_b32_e32 v219, v184, v182, vcc
	v_add_u32_e32 v220, s6, v15
	v_lshlrev_b64 v[152:153], 11, v[2:3]
	v_mov_b32_e32 v155, v65
	v_or_b32_e32 v156, v134, v7
	v_mov_b32_e32 v157, v135
	v_or_b32_e32 v158, 0x1d404000, v1
	v_mov_b32_e32 v159, v65
	v_or_b32_e32 v160, 0x1d403000, v1
	v_mov_b32_e32 v161, v65
	v_lshlrev_b32_e32 v64, 1, v6
	v_lshlrev_b32_e32 v162, 1, v10
	v_lshlrev_b32_e32 v164, 1, v4
	v_lshlrev_b32_e32 v166, 1, v0
	v_mov_b32_e32 v232, v139
	v_mov_b32_e32 v233, v187
	v_mov_b32_e32 v234, v216
	v_mov_b32_e32 v235, v185
	v_mov_b32_e32 v236, v188
	v_mov_b32_e32 v237, v189
	v_mov_b32_e32 v238, v212
	v_mov_b32_e32 v239, v213
	v_mov_b32_e32 v242, v186
	v_add_u32_e32 v240, v217, v218
	v_add_u32_e32 v241, v217, v219
	v_lshrrev_b32_e32 v245, 4, v140
	v_and_b32_e32 v246, 15, v140
	v_lshlrev_b32_e32 v243, 12, v245
	v_lshl_or_b32 v243, v246, 4, v243
	v_and_b32_e32 v245, 0xff, v140
	v_lshlrev_b32_e32 v244, 4, v245
	v_readfirstlane_b32 s23, v140
	s_lshr_b32 s23, s23, 6
	s_load_dwordx2 s[26:27], s[94:95], 0xb8
	s_mov_b32 s20, s89
	s_waitcnt lgkmcnt(0)
; __device__ __forceinline__ unsigned pk2(float lo, float hi) { return f2bf(lo) | (f2bf(hi) << 16); }
; __device__ __forceinline__ void attn_body(const bf16_t* __restrict__ Qb, const bf16_t* __restrict__ KVh, const bf16_t* __restrict__ KR, const float* __restrict__ ropeq,
;                                           bf16_t* __restrict__ Ob, int seq, char* lds, const int tid) {
;     ...
;     { const bf16_t* Qw = Qb + (size_t)(wid * QBLK + r32) * NQ + hi * 8;
; #pragma unroll
;       for (int d0 = 0; d0 < 4; ++d0) qr[d0] = *reinterpret_cast<const bf16x8*>(Qw + d0 * 16);
;       const u32x4 w1 = *reinterpret_cast<const u32x4*>(Qw + 64), w2 = *reinterpret_cast<const u32x4*>(Qw + 80);
;       float x1[8], x2[8]; unpack8(w1, x1); unpack8(w2, x2);
;       const float* rp = ropeq + (size_t)(wid * QBLK + r32) * 32 + hi * 8;
;       float y1[8], y2[8];
; #pragma unroll
;       for (int e = 0; e < 8; ++e) { const float c = rp[e], s = rp[16 + e]; y1[e] = x1[e] * c - x2[e] * s; y2[e] = x1[e] * s + x2[e] * c; }
;       u32x4 o1 = {pk2(y1[0], y1[1]), pk2(y1[2], y1[3]), pk2(y1[4], y1[5]), pk2(y1[6], y1[7])};
;       u32x4 o2 = {pk2(y2[0], y2[1]), pk2(y2[2], y2[3]), pk2(y2[4], y2[5]), pk2(y2[6], y2[7])};
;       qr[4] = *reinterpret_cast<bf16x8*>(&o1); qr[5] = *reinterpret_cast<bf16x8*>(&o2); }
; __device__ __forceinline__ void phase_attn(const Ctx& C, PP p, char* lds_generic) {
;     ...
;     for (int it = C.vcu; it < 2048; it += C.G) {
;         const int qb = it & 15, h = (it >> 4) & 15, b = it >> 8; const size_t t0 = (size_t)b * SEQ, q0 = t0 + qb * 256;
;         __syncthreads();
;         att::attn_body(Q + q0 * NQ + h * 96, KV + t0 * NKV + h * 128, KR + t0 * 32, rope + q0 * 32, O + q0 * DM + h * 64, SEQ, lds_generic, C.tid);
.LA_item:
	s_and_b32 s21, s20, 7
	s_lshr_b32 s10, s20, 3
	s_and_b32 s10, s10, 15
	s_lshr_b32 s11, s20, 7
	s_lshl_b32 s12, s11, 12
	s_lshl_b32 s13, s21, 9
	s_add_u32 s12, s12, s13
	s_lshl_b32 s13, s23, 6
	s_add_u32 s12, s12, s13
	s_mul_i32 s14, s12, 0xc00
	s_mul_i32 s15, s10, 0xc0
	s_add_u32 s14, s14, s15
	s_add_u32 s14, s14, 0xac00000
	s_add_u32 s30, s26, s14
	s_addc_u32 s31, s27, 0
	s_lshl_b32 s14, s12, 7
	s_add_u32 s14, s14, 0x100000
	s_add_u32 s40, s26, s14
	s_addc_u32 s41, s27, 0
	s_lshl_b32 s14, s12, 11
	s_lshl_b32 s15, s10, 7
	s_add_u32 s14, s14, s15
	s_add_u32 s14, s14, 0x6c00000
	s_add_u32 s42, s26, s14
	s_addc_u32 s43, s27, 0
	s_lshl_b32 s14, s11, 24
	s_lshl_b32 s15, s10, 8
	s_add_u32 s14, s14, s15
	s_add_u32 s14, s14, 0x10c00000
	s_add_u32 s28, s26, s14
	s_addc_u32 s29, s27, 0
	s_lshl_b32 s14, s11, 18
	s_add_u32 s14, s14, 0x1d400000
	s_add_u32 s44, s26, s14
	s_addc_u32 s45, s27, 0
	s_barrier
	v_add_u32_e32 v247, 0x20000, v243
	global_load_dwordx4 v[228:231], v243, s[28:29]
	global_load_dwordx4 v[130:133], v247, s[28:29]
	global_load_dwordx4 v[248:251], v244, s[44:45]
	s_add_u32 s28, s28, 0x40000
	s_addc_u32 s29, s29, 0
	s_add_u32 s44, s44, 0x1000
	s_addc_u32 s45, s45, 0
	v_and_b32_e32 v245, 31, v211
	v_lshrrev_b32_e32 v246, 5, v211
	v_mul_u32_u24_e32 v247, 0xc00, v245
	v_lshl_add_u32 v247, v246, 4, v247
	v_lshlrev_b32_e32 v202, 7, v245
	v_lshl_add_u32 v202, v246, 5, v202
	global_load_dwordx4 v[142:145], v247, s[30:31] offset:0
	global_load_dwordx4 v[146:149], v247, s[30:31] offset:32
	global_load_dwordx4 v[150:153], v247, s[30:31] offset:64
	global_load_dwordx4 v[154:157], v247, s[30:31] offset:96
	global_load_dwordx4 v[158:161], v247, s[30:31] offset:128
	global_load_dwordx4 v[162:165], v247, s[30:31] offset:160
	global_load_dwordx4 v[66:69], v202, s[40:41] offset:0
	global_load_dwordx4 v[70:73], v202, s[40:41] offset:16
	global_load_dwordx4 v[74:77], v202, s[40:41] offset:64
	global_load_dwordx4 v[78:81], v202, s[40:41] offset:80
	v_add_u32_e32 v247, 0x18000, v247
	v_add_u32_e32 v202, 0x1000, v202
	global_load_dwordx4 v[166:169], v247, s[30:31] offset:0
	global_load_dwordx4 v[170:173], v247, s[30:31] offset:32
	global_load_dwordx4 v[174:177], v247, s[30:31] offset:64
	global_load_dwordx4 v[178:181], v247, s[30:31] offset:96
	global_load_dwordx4 v[182:185], v247, s[30:31] offset:128
	global_load_dwordx4 v[186:189], v247, s[30:31] offset:160
	global_load_dwordx4 v[98:101], v202, s[40:41] offset:0
	global_load_dwordx4 v[102:105], v202, s[40:41] offset:16
	global_load_dwordx4 v[106:109], v202, s[40:41] offset:64
	global_load_dwordx4 v[110:113], v202, s[40:41] offset:80
	s_waitcnt vmcnt(0)
	v_lshlrev_b32_e32 v82, 16, v158
	v_lshlrev_b32_e32 v83, 16, v162
	v_mul_f32_e32 v84, v83, v74
	v_fma_f32 v86, v82, v66, -v84
	v_mul_f32_e32 v84, v83, v66
	v_fma_f32 v87, v82, v74, v84
	v_and_b32_e32 v82, 0xffff0000, v158
	v_and_b32_e32 v83, 0xffff0000, v162
	v_mul_f32_e32 v84, v83, v75
	v_fma_f32 v85, v82, v67, -v84
	v_cvt_pk_bf16_f32 v158, v86, v85
	v_mul_f32_e32 v84, v83, v67
	v_fma_f32 v85, v82, v75, v84
	v_cvt_pk_bf16_f32 v162, v87, v85
	v_lshlrev_b32_e32 v82, 16, v159
	v_lshlrev_b32_e32 v83, 16, v163
	v_mul_f32_e32 v84, v83, v76
	v_fma_f32 v86, v82, v68, -v84
	v_mul_f32_e32 v84, v83, v68
	v_fma_f32 v87, v82, v76, v84
	v_and_b32_e32 v82, 0xffff0000, v159
	v_and_b32_e32 v83, 0xffff0000, v163
	v_mul_f32_e32 v84, v83, v77
	v_fma_f32 v85, v82, v69, -v84
	v_cvt_pk_bf16_f32 v159, v86, v85
	v_mul_f32_e32 v84, v83, v69
	v_fma_f32 v85, v82, v77, v84
	v_cvt_pk_bf16_f32 v163, v87, v85
	v_lshlrev_b32_e32 v82, 16, v160
	v_lshlrev_b32_e32 v83, 16, v164
	v_mul_f32_e32 v84, v83, v78
	v_fma_f32 v86, v82, v70, -v84
	v_mul_f32_e32 v84, v83, v70
	v_fma_f32 v87, v82, v78, v84
	v_and_b32_e32 v82, 0xffff0000, v160
	v_and_b32_e32 v83, 0xffff0000, v164
	v_mul_f32_e32 v84, v83, v79
	v_fma_f32 v85, v82, v71, -v84
	v_cvt_pk_bf16_f32 v160, v86, v85
	v_mul_f32_e32 v84, v83, v71
	v_fma_f32 v85, v82, v79, v84
	v_cvt_pk_bf16_f32 v164, v87, v85
	v_lshlrev_b32_e32 v82, 16, v161
	v_lshlrev_b32_e32 v83, 16, v165
	v_mul_f32_e32 v84, v83, v80
	v_fma_f32 v86, v82, v72, -v84
	v_mul_f32_e32 v84, v83, v72
	v_fma_f32 v87, v82, v80, v84
	v_and_b32_e32 v82, 0xffff0000, v161
	v_and_b32_e32 v83, 0xffff0000, v165
	v_mul_f32_e32 v84, v83, v81
	v_fma_f32 v85, v82, v73, -v84
	v_cvt_pk_bf16_f32 v161, v86, v85
	v_mul_f32_e32 v84, v83, v73
	v_fma_f32 v85, v82, v81, v84
	v_cvt_pk_bf16_f32 v165, v87, v85
	v_lshlrev_b32_e32 v114, 16, v182
	v_lshlrev_b32_e32 v115, 16, v186
	v_mul_f32_e32 v116, v115, v106
	v_fma_f32 v118, v114, v98, -v116
	v_mul_f32_e32 v116, v115, v98
	v_fma_f32 v119, v114, v106, v116
	v_and_b32_e32 v114, 0xffff0000, v182
	v_and_b32_e32 v115, 0xffff0000, v186
	v_mul_f32_e32 v116, v115, v107
	v_fma_f32 v117, v114, v99, -v116
	v_cvt_pk_bf16_f32 v182, v118, v117
	v_mul_f32_e32 v116, v115, v99
	v_fma_f32 v117, v114, v107, v116
	v_cvt_pk_bf16_f32 v186, v119, v117
	v_lshlrev_b32_e32 v114, 16, v183
	v_lshlrev_b32_e32 v115, 16, v187
	v_mul_f32_e32 v116, v115, v108
	v_fma_f32 v118, v114, v100, -v116
	v_mul_f32_e32 v116, v115, v100
	v_fma_f32 v119, v114, v108, v116
	v_and_b32_e32 v114, 0xffff0000, v183
	v_and_b32_e32 v115, 0xffff0000, v187
	v_mul_f32_e32 v116, v115, v109
	v_fma_f32 v117, v114, v101, -v116
	v_cvt_pk_bf16_f32 v183, v118, v117
	v_mul_f32_e32 v116, v115, v101
	v_fma_f32 v117, v114, v109, v116
	v_cvt_pk_bf16_f32 v187, v119, v117
	v_lshlrev_b32_e32 v114, 16, v184
	v_lshlrev_b32_e32 v115, 16, v188
	v_mul_f32_e32 v116, v115, v110
	v_fma_f32 v118, v114, v102, -v116
	v_mul_f32_e32 v116, v115, v102
	v_fma_f32 v119, v114, v110, v116
	v_and_b32_e32 v114, 0xffff0000, v184
	v_and_b32_e32 v115, 0xffff0000, v188
	v_mul_f32_e32 v116, v115, v111
	v_fma_f32 v117, v114, v103, -v116
	v_cvt_pk_bf16_f32 v184, v118, v117
	v_mul_f32_e32 v116, v115, v103
	v_fma_f32 v117, v114, v111, v116
	v_cvt_pk_bf16_f32 v188, v119, v117
	v_lshlrev_b32_e32 v114, 16, v185
	v_lshlrev_b32_e32 v115, 16, v189
	v_mul_f32_e32 v116, v115, v112
	v_fma_f32 v118, v114, v104, -v116
	v_mul_f32_e32 v116, v115, v104
	v_fma_f32 v119, v114, v112, v116
	v_and_b32_e32 v114, 0xffff0000, v185
	v_and_b32_e32 v115, 0xffff0000, v189
	v_mul_f32_e32 v116, v115, v113
	v_fma_f32 v117, v114, v105, -v116
	v_cvt_pk_bf16_f32 v185, v118, v117
	v_mul_f32_e32 v116, v115, v105
	v_fma_f32 v117, v114, v113, v116
	v_cvt_pk_bf16_f32 v189, v119, v117
	s_mov_b32 s18, 0
	s_mov_b32 s19, 0x4000
	s_mov_b32 s22, 0x8000
	s_mov_b32 s16, 0
	s_waitcnt vmcnt(0)
	v_add_u32_e32 v246, s18, v240
	v_add_u32_e32 v245, s18, v241
	ds_write_b128 v246, v[228:231]
	ds_write_b128 v245, v[130:133]
	s_cmp_eq_u64 s[2:3], 0
	s_cbranch_scc1 .LA_swp
	v_add_u32_e32 v245, s18, v242
	ds_write_b128 v245, v[248:251] offset:49152
; #define SLOAD(i, k0) do { sr_[i].a0 = *reinterpret_cast<const bf16x8*>(&KVh[(size_t)((k0) + sr) * NKV + c16 * 8]); sr_[i].a1 = *reinterpret_cast<const bf16x8*>(&KVh[(size_t)((k0) + 32 + sr) * NKV + c16 * 8]); \
;     sr_[i].rr = *reinterpret_cast<const bf16x8*>(&KR[(size_t)((k0) + rkey) * 32 + rch * 8]); } while (0)
; #define SWRITE(b, i) do { if (isK) { *(bf16x8*)(K_lds + (b) * SHM_K + kst0) = sr_[i].a0; *(bf16x8*)(K_lds + (b) * SHM_K + kst1) = sr_[i].a1; } \
;     else { *(bf16x8*)(V_lds + (b) * SHM_V + vst0) = sr_[i].a0; *(bf16x8*)(V_lds + (b) * SHM_V + vst1) = sr_[i].a1; } \
;     if (rwr) *(bf16x8*)(K_lds + (b) * SHM_K + rst) = sr_[i].rr; } while (0)
; #define SWAIT() asm volatile("s_waitcnt vmcnt(3)" ::: "memory")
; __device__ __forceinline__ void qkt(f32x16& p0, f32x16& p1, const char* Ks, const bf16x8* qr, int r32, int hi) {
;     p0 = f32x16{}; p1 = f32x16{};
; #pragma unroll
;     for (int d0 = 0; d0 < 6; ++d0) { const int cb = (d0 * 16 + hi * 8) * 2;
;         bf16x8 b0 = *reinterpret_cast<const bf16x8*>(Ks + KSWZ(r32, cb));
;         bf16x8 b1 = *reinterpret_cast<const bf16x8*>(Ks + KSWZ(32 + r32, cb));
;         p0 = __builtin_amdgcn_mfma_f32_32x32x16_bf16(b0, qr[d0], p0, 0, 0, 0);
;         p1 = __builtin_amdgcn_mfma_f32_32x32x16_bf16(b1, qr[d0], p1, 0, 0, 0); }
; __device__ __forceinline__ void attn_body(const bf16_t* __restrict__ Qb, const bf16_t* __restrict__ KVh, const bf16_t* __restrict__ KR, const float* __restrict__ ropeq,
;                                           bf16_t* __restrict__ Ob, int seq, char* lds, const int tid) {
;     ...
;     f32x16 pA0, pA1, pB0, pB1; float mnA, mnB, alA, alB; bf16x8 pa0, pa1, pa2, pa3; const int NT = seq / KVBLK;
;     constexpr int SE = 0, SO = 1;
;     SLOAD(SE, 0); asm volatile("s_waitcnt vmcnt(0)" ::: "memory"); SWRITE(0, SE); __syncthreads();
;     qkt(pA0, pA1, K_lds, qr, r32, hi); partialSM(pA0, pA1, m_reg, mnA, alA);
;     SLOAD(SO, KVBLK); if (2 < NT) SLOAD(SE, 2 * KVBLK);
;     SWAIT(); SWRITE(1, SO); __syncthreads();
;     int bp = 0, bc = 1, bn = 2;
;     for (int j = 1; j + 1 < NT; j += 2) {
.LA_swp:
	v_add_u32_e32 v247, 0x20000, v243
	global_load_dwordx4 v[228:231], v243, s[28:29]
	global_load_dwordx4 v[130:133], v247, s[28:29]
	global_load_dwordx4 v[248:251], v244, s[44:45]
	s_add_u32 s28, s28, 0x40000
	s_addc_u32 s29, s29, 0
	s_add_u32 s44, s44, 0x1000
	s_addc_u32 s45, s45, 0
	v_mov_b32_e32 v141, 0xf149f2ca
	v_mov_b32_e32 v254, 0
	v_mov_b32_e32 v0, 0
	v_mov_b32_e32 v1, 0
	v_mov_b32_e32 v2, 0
	v_mov_b32_e32 v3, 0
	v_mov_b32_e32 v4, 0
	v_mov_b32_e32 v5, 0
	v_mov_b32_e32 v6, 0
	v_mov_b32_e32 v7, 0
	v_mov_b32_e32 v8, 0
	v_mov_b32_e32 v9, 0
	v_mov_b32_e32 v10, 0
	v_mov_b32_e32 v11, 0
	v_mov_b32_e32 v12, 0
	v_mov_b32_e32 v13, 0
	v_mov_b32_e32 v14, 0
	v_mov_b32_e32 v15, 0
	v_mov_b32_e32 v16, 0
	v_mov_b32_e32 v17, 0
	v_mov_b32_e32 v18, 0
	v_mov_b32_e32 v19, 0
	v_mov_b32_e32 v20, 0
	v_mov_b32_e32 v21, 0
	v_mov_b32_e32 v22, 0
	v_mov_b32_e32 v23, 0
	v_mov_b32_e32 v24, 0
	v_mov_b32_e32 v25, 0
	v_mov_b32_e32 v26, 0
	v_mov_b32_e32 v27, 0
	v_mov_b32_e32 v28, 0
	v_mov_b32_e32 v29, 0
	v_mov_b32_e32 v30, 0
	v_mov_b32_e32 v31, 0
	v_mov_b32_e32 v139, 0xf149f2ca
	v_mov_b32_e32 v255, 0
	v_mov_b32_e32 v32, 0
	v_mov_b32_e32 v33, 0
	v_mov_b32_e32 v34, 0
	v_mov_b32_e32 v35, 0
	v_mov_b32_e32 v36, 0
	v_mov_b32_e32 v37, 0
	v_mov_b32_e32 v38, 0
	v_mov_b32_e32 v39, 0
	v_mov_b32_e32 v40, 0
	v_mov_b32_e32 v41, 0
	v_mov_b32_e32 v42, 0
	v_mov_b32_e32 v43, 0
	v_mov_b32_e32 v44, 0
	v_mov_b32_e32 v45, 0
	v_mov_b32_e32 v46, 0
	v_mov_b32_e32 v47, 0
	v_mov_b32_e32 v48, 0
	v_mov_b32_e32 v49, 0
	v_mov_b32_e32 v50, 0
	v_mov_b32_e32 v51, 0
	v_mov_b32_e32 v52, 0
	v_mov_b32_e32 v53, 0
	v_mov_b32_e32 v54, 0
	v_mov_b32_e32 v55, 0
	v_mov_b32_e32 v56, 0
	v_mov_b32_e32 v57, 0
	v_mov_b32_e32 v58, 0
	v_mov_b32_e32 v59, 0
	v_mov_b32_e32 v60, 0
	v_mov_b32_e32 v61, 0
	v_mov_b32_e32 v62, 0
	v_mov_b32_e32 v63, 0
	s_waitcnt lgkmcnt(0)
	s_barrier
.LA_loop:
	v_add_u32_e32 v247, s18, v236
	ds_read_b128 v[212:215], v247 offset:49152
	ds_read_b128 v[216:219], v247 offset:57344
	v_add_u32_e32 v247, s18, v237
	ds_read_b128 v[220:223], v247 offset:49152
	ds_read_b128 v[224:227], v247 offset:57344
	s_cmp_gt_u32 s16, 62
	s_cbranch_scc1 .LA_nosw
	s_waitcnt vmcnt(0)
	v_add_u32_e32 v246, s19, v240
	v_add_u32_e32 v245, s19, v241
	ds_write_b128 v246, v[228:231]
	ds_write_b128 v245, v[130:133]
	s_cmp_eq_u64 s[2:3], 0
	s_cbranch_scc1 .LA_swl
	v_add_u32_e32 v245, s19, v242
	ds_write_b128 v245, v[248:251] offset:49152
.LA_swl:
	s_cmp_gt_u32 s16, 61
	s_cbranch_scc1 .LA_nosw
	v_add_u32_e32 v247, 0x20000, v243
	global_load_dwordx4 v[228:231], v243, s[28:29]
	global_load_dwordx4 v[130:133], v247, s[28:29]
	global_load_dwordx4 v[248:251], v244, s[44:45]
	s_add_u32 s28, s28, 0x40000
	s_addc_u32 s29, s29, 0
	s_add_u32 s44, s44, 0x1000
	s_addc_u32 s45, s45, 0
.LA_nosw:
	s_waitcnt lgkmcnt(2)
	v_mfma_f32_32x32x16_bf16 v[66:81], v[212:215], v[142:145], 0
	v_mfma_f32_32x32x16_bf16 v[82:97], v[216:219], v[142:145], 0
	v_mfma_f32_32x32x16_bf16 v[98:113], v[212:215], v[166:169], 0
	v_mfma_f32_32x32x16_bf16 v[114:129], v[216:219], v[166:169], 0
	v_add_u32_e32 v247, s18, v238
	ds_read_b128 v[212:215], v247 offset:49152
	ds_read_b128 v[216:219], v247 offset:57344
	s_waitcnt lgkmcnt(2)
	v_mfma_f32_32x32x16_bf16 v[66:81], v[220:223], v[146:149], v[66:81]
	v_mfma_f32_32x32x16_bf16 v[82:97], v[224:227], v[146:149], v[82:97]
	v_mfma_f32_32x32x16_bf16 v[98:113], v[220:223], v[170:173], v[98:113]
	v_mfma_f32_32x32x16_bf16 v[114:129], v[224:227], v[170:173], v[114:129]
	v_add_u32_e32 v247, s18, v239
	ds_read_b128 v[220:223], v247 offset:49152
	ds_read_b128 v[224:227], v247 offset:57344
	s_waitcnt lgkmcnt(2)
	v_mfma_f32_32x32x16_bf16 v[66:81], v[212:215], v[150:153], v[66:81]
	v_mfma_f32_32x32x16_bf16 v[82:97], v[216:219], v[150:153], v[82:97]
	v_mfma_f32_32x32x16_bf16 v[98:113], v[212:215], v[174:177], v[98:113]
	v_mfma_f32_32x32x16_bf16 v[114:129], v[216:219], v[174:177], v[114:129]
	v_add_u32_e32 v247, s18, v236
	ds_read_b128 v[212:215], v247 offset:49280
	ds_read_b128 v[216:219], v247 offset:57472
	s_waitcnt lgkmcnt(2)
	v_mfma_f32_32x32x16_bf16 v[66:81], v[220:223], v[154:157], v[66:81]
	v_mfma_f32_32x32x16_bf16 v[82:97], v[224:227], v[154:157], v[82:97]
	v_mfma_f32_32x32x16_bf16 v[98:113], v[220:223], v[178:181], v[98:113]
	v_mfma_f32_32x32x16_bf16 v[114:129], v[224:227], v[178:181], v[114:129]
	v_add_u32_e32 v247, s18, v237
	ds_read_b128 v[220:223], v247 offset:49280
	ds_read_b128 v[224:227], v247 offset:57472
	s_waitcnt lgkmcnt(2)
	v_mfma_f32_32x32x16_bf16 v[66:81], v[212:215], v[158:161], v[66:81]
	v_mfma_f32_32x32x16_bf16 v[82:97], v[216:219], v[158:161], v[82:97]
	v_mfma_f32_32x32x16_bf16 v[98:113], v[212:215], v[182:185], v[98:113]
	v_mfma_f32_32x32x16_bf16 v[114:129], v[216:219], v[182:185], v[114:129]
	s_waitcnt lgkmcnt(0)
; __device__ __forceinline__ void partialSM(f32x16& p0, f32x16& p1, float& m_reg, float& mn, float& alpha) {
;     constexpr float Cc = SCALE * 1.4426950408889634f;
;     float pmax = p0[0];
; #pragma unroll
;     for (int r = 1; r < 16; ++r) pmax = fmaxf(pmax, p0[r]);
; #pragma unroll
;     for (int r = 0; r < 16; ++r) pmax = fmaxf(pmax, p1[r]);
;     { auto rr = __builtin_amdgcn_permlane32_swap(__float_as_uint(pmax), __float_as_uint(pmax), false, false);
;       pmax = fmaxf(__uint_as_float(rr[0]), __uint_as_float(rr[1])); }
;     if (__builtin_expect(__all(pmax - m_reg <= THR / SCALE), 1)) { mn = m_reg; alpha = 1.f; }
;     else { mn = fmaxf(m_reg, pmax); alpha = __builtin_amdgcn_exp2f((m_reg - mn) * Cc); m_reg = mn; }
;     const float mnC = -mn * Cc;
;     { typedef float f32x2 __attribute__((ext_vector_type(2))); const f32x2 c2 = {Cc, Cc}, m2 = {mnC, mnC};
; #pragma unroll
;       for (int r = 0; r < 16; r += 2) { f32x2 t = {p0[r], p0[r + 1]}; t = __builtin_elementwise_fma(t, c2, m2); p0[r] = t.x; p0[r + 1] = t.y; }
; #pragma unroll
;       for (int r = 0; r < 16; r += 2) { f32x2 t = {p1[r], p1[r + 1]}; t = __builtin_elementwise_fma(t, c2, m2); p1[r] = t.x; p1[r + 1] = t.y; } }
; #pragma unroll
;     for (int r = 0; r < 16; ++r) p0[r] = __builtin_amdgcn_exp2f(p0[r]);
; }
; __device__ __forceinline__ void finishSM(f32x16& p0, f32x16& p1, float alpha, float& l_reg, bf16x8& pa0, bf16x8& pa1, bf16x8& pa2, bf16x8& pa3) {
; #pragma unroll
;     for (int r = 0; r < 16; ++r) p1[r] = __builtin_amdgcn_exp2f(p1[r]);
;     float ps;
;     { typedef float f32x2 __attribute__((ext_vector_type(2))); f32x2 s0 = {p0[0], p0[1]}, s1 = {p1[0], p1[1]};
; #pragma unroll
;       for (int r = 2; r < 16; r += 2) { s0 += (f32x2){p0[r], p0[r + 1]}; s1 += (f32x2){p1[r], p1[r + 1]}; }
;       s0 += s1; ps = s0.x + s0.y; }
;     { auto rr = __builtin_amdgcn_permlane32_swap(__float_as_uint(ps), __float_as_uint(ps), false, false);
;       ps = __uint_as_float(rr[0]) + __uint_as_float(rr[1]); }
;     l_reg = l_reg * alpha + ps;
;     ...
;     PK4(p0, 0, pa0); PK4(p0, 8, pa1); PK4(p1, 0, pa2); PK4(p1, 8, pa3);
	v_mfma_f32_32x32x16_bf16 v[66:81], v[220:223], v[162:165], v[66:81]
	v_mfma_f32_32x32x16_bf16 v[82:97], v[224:227], v[162:165], v[82:97]
	v_mfma_f32_32x32x16_bf16 v[98:113], v[220:223], v[186:189], v[98:113]
	v_mfma_f32_32x32x16_bf16 v[114:129], v[224:227], v[186:189], v[114:129]
	s_nop 7
	s_nop 0
	v_max_f32_e32 v212, v66, v67
	v_max_f32_e32 v213, v82, v83
	v_max3_f32 v212, v212, v68, v69
	v_max3_f32 v213, v213, v84, v85
	v_max3_f32 v212, v212, v70, v71
	v_max3_f32 v213, v213, v86, v87
	v_max3_f32 v212, v212, v72, v73
	v_max3_f32 v213, v213, v88, v89
	v_max3_f32 v212, v212, v74, v75
	v_max3_f32 v213, v213, v90, v91
	v_max3_f32 v212, v212, v76, v77
	v_max3_f32 v213, v213, v92, v93
	v_max3_f32 v212, v212, v78, v79
	v_max3_f32 v213, v213, v94, v95
	v_max3_f32 v212, v212, v80, v81
	v_max3_f32 v213, v213, v96, v97
	v_max_f32_e32 v212, v212, v213
	v_mov_b32_e32 v213, v212
	s_nop 1
	v_permlane32_swap_b32_e32 v212, v213
	v_max_f32_e32 v212, v212, v213
	v_sub_f32_e32 v214, v212, v141
	v_cmp_ge_f32_e32 vcc, s67, v214
	v_max_f32_e32 v212, v141, v212
	v_sub_f32_e32 v214, v141, v212
	v_mul_f32_e32 v214, 0x3e16c740, v214
	v_exp_f32_e32 v215, v214
	s_cmp_eq_u64 vcc, exec
	s_cselect_b64 s[58:59], -1, 0
	v_cndmask_b32_e64 v141, v212, v141, s[58:59]
	v_cndmask_b32_e64 v215, v215, 1.0, s[58:59]
	v_mul_f32_e32 v216, 0xbe16c740, v141
	v_fma_f32 v66, v66, s52, v216
	v_fma_f32 v67, v67, s52, v216
	v_fma_f32 v68, v68, s52, v216
	v_fma_f32 v69, v69, s52, v216
	v_fma_f32 v70, v70, s52, v216
	v_fma_f32 v71, v71, s52, v216
	v_fma_f32 v72, v72, s52, v216
	v_fma_f32 v73, v73, s52, v216
	v_fma_f32 v74, v74, s52, v216
	v_fma_f32 v75, v75, s52, v216
	v_fma_f32 v76, v76, s52, v216
	v_fma_f32 v77, v77, s52, v216
	v_fma_f32 v78, v78, s52, v216
	v_fma_f32 v79, v79, s52, v216
	v_fma_f32 v80, v80, s52, v216
	v_fma_f32 v81, v81, s52, v216
	v_fma_f32 v82, v82, s52, v216
	v_fma_f32 v83, v83, s52, v216
	v_fma_f32 v84, v84, s52, v216
	v_fma_f32 v85, v85, s52, v216
	v_fma_f32 v86, v86, s52, v216
	v_fma_f32 v87, v87, s52, v216
	v_fma_f32 v88, v88, s52, v216
	v_fma_f32 v89, v89, s52, v216
	v_fma_f32 v90, v90, s52, v216
	v_fma_f32 v91, v91, s52, v216
	v_fma_f32 v92, v92, s52, v216
	v_fma_f32 v93, v93, s52, v216
	v_fma_f32 v94, v94, s52, v216
	v_fma_f32 v95, v95, s52, v216
	v_fma_f32 v96, v96, s52, v216
	v_fma_f32 v97, v97, s52, v216
	v_exp_f32_e32 v66, v66
	v_exp_f32_e32 v67, v67
	v_exp_f32_e32 v68, v68
	v_exp_f32_e32 v69, v69
	v_exp_f32_e32 v70, v70
	v_exp_f32_e32 v71, v71
	v_exp_f32_e32 v72, v72
	v_exp_f32_e32 v73, v73
	v_exp_f32_e32 v74, v74
	v_exp_f32_e32 v75, v75
	v_exp_f32_e32 v76, v76
	v_exp_f32_e32 v77, v77
	v_exp_f32_e32 v78, v78
	v_exp_f32_e32 v79, v79
	v_exp_f32_e32 v80, v80
	v_exp_f32_e32 v81, v81
	v_exp_f32_e32 v82, v82
	v_exp_f32_e32 v83, v83
	v_exp_f32_e32 v84, v84
	v_exp_f32_e32 v85, v85
	v_exp_f32_e32 v86, v86
	v_exp_f32_e32 v87, v87
	v_exp_f32_e32 v88, v88
	v_exp_f32_e32 v89, v89
	v_exp_f32_e32 v90, v90
	v_exp_f32_e32 v91, v91
	v_exp_f32_e32 v92, v92
	v_exp_f32_e32 v93, v93
	v_exp_f32_e32 v94, v94
	v_exp_f32_e32 v95, v95
	v_exp_f32_e32 v96, v96
	v_exp_f32_e32 v97, v97
	v_add_f32_e32 v212, v66, v68
	v_add_f32_e32 v213, v67, v69
	v_add_f32_e32 v212, v70, v212
	v_add_f32_e32 v213, v71, v213
	v_add_f32_e32 v212, v72, v212
	v_add_f32_e32 v213, v73, v213
	v_add_f32_e32 v212, v74, v212
	v_add_f32_e32 v213, v75, v213
	v_add_f32_e32 v212, v76, v212
	v_add_f32_e32 v213, v77, v213
	v_add_f32_e32 v212, v78, v212
	v_add_f32_e32 v213, v79, v213
	v_add_f32_e32 v212, v80, v212
	v_add_f32_e32 v213, v81, v213
	v_add_f32_e32 v212, v82, v212
	v_add_f32_e32 v213, v83, v213
	v_add_f32_e32 v212, v84, v212
	v_add_f32_e32 v213, v85, v213
	v_add_f32_e32 v212, v86, v212
	v_add_f32_e32 v213, v87, v213
	v_add_f32_e32 v212, v88, v212
	v_add_f32_e32 v213, v89, v213
	v_add_f32_e32 v212, v90, v212
	v_add_f32_e32 v213, v91, v213
	v_add_f32_e32 v212, v92, v212
	v_add_f32_e32 v213, v93, v213
	v_add_f32_e32 v212, v94, v212
	v_add_f32_e32 v213, v95, v213
	v_add_f32_e32 v212, v96, v212
	v_add_f32_e32 v213, v97, v213
	v_add_f32_e32 v212, v212, v213
	v_fma_f32 v254, v254, v215, v212
	v_cvt_pk_bf16_f32 v66, v66, v67
	v_cvt_pk_bf16_f32 v67, v68, v69
	v_cvt_pk_bf16_f32 v68, v70, v71
	v_cvt_pk_bf16_f32 v69, v72, v73
	v_cvt_pk_bf16_f32 v70, v74, v75
	v_cvt_pk_bf16_f32 v71, v76, v77
	v_cvt_pk_bf16_f32 v72, v78, v79
	v_cvt_pk_bf16_f32 v73, v80, v81
	v_cvt_pk_bf16_f32 v82, v82, v83
	v_cvt_pk_bf16_f32 v83, v84, v85
	v_cvt_pk_bf16_f32 v84, v86, v87
	v_cvt_pk_bf16_f32 v85, v88, v89
	v_cvt_pk_bf16_f32 v86, v90, v91
	v_cvt_pk_bf16_f32 v87, v92, v93
	v_cvt_pk_bf16_f32 v88, v94, v95
	v_cvt_pk_bf16_f32 v89, v96, v97
	v_permlane32_swap_b32_e32 v66, v68
	v_permlane32_swap_b32_e32 v67, v69
	v_permlane32_swap_b32_e32 v70, v72
	v_permlane32_swap_b32_e32 v71, v73
	v_permlane32_swap_b32_e32 v82, v84
	v_permlane32_swap_b32_e32 v83, v85
	v_permlane32_swap_b32_e32 v86, v88
	v_permlane32_swap_b32_e32 v87, v89
	v_cmp_gt_f32_e32 vcc, 1.0, v215
	s_cbranch_vccz .LA_rs0
	s_and_saveexec_b64 s[60:61], s[4:5]
	ds_write_b32 v234, v215 offset:128
	s_or_b64 exec, exec, s[60:61]
	s_waitcnt lgkmcnt(0)
	v_add_u32_e32 v245, v232, v233
	ds_read_b128 v[220:223], v245 offset:224
	ds_read_b128 v[224:227], v245 offset:192
	ds_read_b128 v[216:219], v245 offset:160
	ds_read_b128 v[212:215], v245 offset:128
	s_waitcnt lgkmcnt(0)
	v_mul_f32_e32 v12, v12, v220
	v_mul_f32_e32 v13, v13, v221
	v_mul_f32_e32 v14, v14, v222
	v_mul_f32_e32 v15, v15, v223
	v_mul_f32_e32 v8, v8, v224
	v_mul_f32_e32 v9, v9, v225
	v_mul_f32_e32 v10, v10, v226
	v_mul_f32_e32 v11, v11, v227
	v_mul_f32_e32 v4, v4, v216
	v_mul_f32_e32 v5, v5, v217
	v_mul_f32_e32 v6, v6, v218
	v_mul_f32_e32 v7, v7, v219
	v_mul_f32_e32 v0, v0, v212
	v_mul_f32_e32 v1, v1, v213
	v_mul_f32_e32 v2, v2, v214
	v_mul_f32_e32 v3, v3, v215
	v_mul_f32_e32 v28, v28, v220
	v_mul_f32_e32 v29, v29, v221
	v_mul_f32_e32 v30, v30, v222
	v_mul_f32_e32 v31, v31, v223
	v_mul_f32_e32 v24, v24, v224
	v_mul_f32_e32 v25, v25, v225
	v_mul_f32_e32 v26, v26, v226
	v_mul_f32_e32 v27, v27, v227
	v_mul_f32_e32 v20, v20, v216
	v_mul_f32_e32 v21, v21, v217
	v_mul_f32_e32 v22, v22, v218
	v_mul_f32_e32 v23, v23, v219
	v_mul_f32_e32 v16, v16, v212
	v_mul_f32_e32 v17, v17, v213
	v_mul_f32_e32 v18, v18, v214
	v_mul_f32_e32 v19, v19, v215
; __device__ __forceinline__ void partialSM(f32x16& p0, f32x16& p1, float& m_reg, float& mn, float& alpha) {
;     constexpr float Cc = SCALE * 1.4426950408889634f;
;     float pmax = p0[0];
; #pragma unroll
;     for (int r = 1; r < 16; ++r) pmax = fmaxf(pmax, p0[r]);
; #pragma unroll
;     for (int r = 0; r < 16; ++r) pmax = fmaxf(pmax, p1[r]);
;     { auto rr = __builtin_amdgcn_permlane32_swap(__float_as_uint(pmax), __float_as_uint(pmax), false, false);
;       pmax = fmaxf(__uint_as_float(rr[0]), __uint_as_float(rr[1])); }
;     if (__builtin_expect(__all(pmax - m_reg <= THR / SCALE), 1)) { mn = m_reg; alpha = 1.f; }
;     else { mn = fmaxf(m_reg, pmax); alpha = __builtin_amdgcn_exp2f((m_reg - mn) * Cc); m_reg = mn; }
;     const float mnC = -mn * Cc;
;     { typedef float f32x2 __attribute__((ext_vector_type(2))); const f32x2 c2 = {Cc, Cc}, m2 = {mnC, mnC};
; #pragma unroll
;       for (int r = 0; r < 16; r += 2) { f32x2 t = {p0[r], p0[r + 1]}; t = __builtin_elementwise_fma(t, c2, m2); p0[r] = t.x; p0[r + 1] = t.y; }
; #pragma unroll
;       for (int r = 0; r < 16; r += 2) { f32x2 t = {p1[r], p1[r + 1]}; t = __builtin_elementwise_fma(t, c2, m2); p1[r] = t.x; p1[r + 1] = t.y; } }
; #pragma unroll
;     for (int r = 0; r < 16; ++r) p0[r] = __builtin_amdgcn_exp2f(p0[r]);
; }
; __device__ __forceinline__ void finishSM(f32x16& p0, f32x16& p1, float alpha, float& l_reg, bf16x8& pa0, bf16x8& pa1, bf16x8& pa2, bf16x8& pa3) {
; #pragma unroll
;     for (int r = 0; r < 16; ++r) p1[r] = __builtin_amdgcn_exp2f(p1[r]);
;     float ps;
;     { typedef float f32x2 __attribute__((ext_vector_type(2))); f32x2 s0 = {p0[0], p0[1]}, s1 = {p1[0], p1[1]};
; #pragma unroll
;       for (int r = 2; r < 16; r += 2) { s0 += (f32x2){p0[r], p0[r + 1]}; s1 += (f32x2){p1[r], p1[r + 1]}; }
;       s0 += s1; ps = s0.x + s0.y; }
;     { auto rr = __builtin_amdgcn_permlane32_swap(__float_as_uint(ps), __float_as_uint(ps), false, false);
;       ps = __uint_as_float(rr[0]) + __uint_as_float(rr[1]); }
;     l_reg = l_reg * alpha + ps;
;     ...
;     PK4(p0, 0, pa0); PK4(p0, 8, pa1); PK4(p1, 0, pa2); PK4(p1, 8, pa3);
;     ...
; }
.LA_rs0:
	v_max_f32_e32 v212, v98, v99
	v_max_f32_e32 v213, v114, v115
	v_max3_f32 v212, v212, v100, v101
	v_max3_f32 v213, v213, v116, v117
	v_max3_f32 v212, v212, v102, v103
	v_max3_f32 v213, v213, v118, v119
	v_max3_f32 v212, v212, v104, v105
	v_max3_f32 v213, v213, v120, v121
	v_max3_f32 v212, v212, v106, v107
	v_max3_f32 v213, v213, v122, v123
	v_max3_f32 v212, v212, v108, v109
	v_max3_f32 v213, v213, v124, v125
	v_max3_f32 v212, v212, v110, v111
	v_max3_f32 v213, v213, v126, v127
	v_max3_f32 v212, v212, v112, v113
	v_max3_f32 v213, v213, v128, v129
	v_max_f32_e32 v212, v212, v213
	v_mov_b32_e32 v213, v212
	s_nop 1
	v_permlane32_swap_b32_e32 v212, v213
	v_max_f32_e32 v212, v212, v213
	v_sub_f32_e32 v214, v212, v139
	v_cmp_ge_f32_e32 vcc, s67, v214
	v_max_f32_e32 v212, v139, v212
	v_sub_f32_e32 v214, v139, v212
	v_mul_f32_e32 v214, 0x3e16c740, v214
	v_exp_f32_e32 v215, v214
	s_cmp_eq_u64 vcc, exec
	s_cselect_b64 s[58:59], -1, 0
	v_cndmask_b32_e64 v139, v212, v139, s[58:59]
	v_cndmask_b32_e64 v215, v215, 1.0, s[58:59]
	v_mul_f32_e32 v216, 0xbe16c740, v139
	v_fma_f32 v98, v98, s52, v216
	v_fma_f32 v99, v99, s52, v216
	v_fma_f32 v100, v100, s52, v216
	v_fma_f32 v101, v101, s52, v216
	v_fma_f32 v102, v102, s52, v216
	v_fma_f32 v103, v103, s52, v216
	v_fma_f32 v104, v104, s52, v216
	v_fma_f32 v105, v105, s52, v216
	v_fma_f32 v106, v106, s52, v216
	v_fma_f32 v107, v107, s52, v216
	v_fma_f32 v108, v108, s52, v216
	v_fma_f32 v109, v109, s52, v216
	v_fma_f32 v110, v110, s52, v216
	v_fma_f32 v111, v111, s52, v216
	v_fma_f32 v112, v112, s52, v216
	v_fma_f32 v113, v113, s52, v216
	v_fma_f32 v114, v114, s52, v216
	v_fma_f32 v115, v115, s52, v216
	v_fma_f32 v116, v116, s52, v216
	v_fma_f32 v117, v117, s52, v216
	v_fma_f32 v118, v118, s52, v216
	v_fma_f32 v119, v119, s52, v216
	v_fma_f32 v120, v120, s52, v216
	v_fma_f32 v121, v121, s52, v216
	v_fma_f32 v122, v122, s52, v216
	v_fma_f32 v123, v123, s52, v216
	v_fma_f32 v124, v124, s52, v216
	v_fma_f32 v125, v125, s52, v216
	v_fma_f32 v126, v126, s52, v216
	v_fma_f32 v127, v127, s52, v216
	v_fma_f32 v128, v128, s52, v216
	v_fma_f32 v129, v129, s52, v216
	v_exp_f32_e32 v98, v98
	v_exp_f32_e32 v99, v99
	v_exp_f32_e32 v100, v100
	v_exp_f32_e32 v101, v101
	v_exp_f32_e32 v102, v102
	v_exp_f32_e32 v103, v103
	v_exp_f32_e32 v104, v104
	v_exp_f32_e32 v105, v105
	v_exp_f32_e32 v106, v106
	v_exp_f32_e32 v107, v107
	v_exp_f32_e32 v108, v108
	v_exp_f32_e32 v109, v109
	v_exp_f32_e32 v110, v110
	v_exp_f32_e32 v111, v111
	v_exp_f32_e32 v112, v112
	v_exp_f32_e32 v113, v113
	v_exp_f32_e32 v114, v114
	v_exp_f32_e32 v115, v115
	v_exp_f32_e32 v116, v116
	v_exp_f32_e32 v117, v117
	v_exp_f32_e32 v118, v118
	v_exp_f32_e32 v119, v119
	v_exp_f32_e32 v120, v120
	v_exp_f32_e32 v121, v121
	v_exp_f32_e32 v122, v122
	v_exp_f32_e32 v123, v123
	v_exp_f32_e32 v124, v124
	v_exp_f32_e32 v125, v125
	v_exp_f32_e32 v126, v126
	v_exp_f32_e32 v127, v127
	v_exp_f32_e32 v128, v128
	v_exp_f32_e32 v129, v129
	v_add_f32_e32 v212, v98, v100
	v_add_f32_e32 v213, v99, v101
	v_add_f32_e32 v212, v102, v212
	v_add_f32_e32 v213, v103, v213
	v_add_f32_e32 v212, v104, v212
	v_add_f32_e32 v213, v105, v213
	v_add_f32_e32 v212, v106, v212
	v_add_f32_e32 v213, v107, v213
	v_add_f32_e32 v212, v108, v212
	v_add_f32_e32 v213, v109, v213
	v_add_f32_e32 v212, v110, v212
	v_add_f32_e32 v213, v111, v213
	v_add_f32_e32 v212, v112, v212
	v_add_f32_e32 v213, v113, v213
	v_add_f32_e32 v212, v114, v212
	v_add_f32_e32 v213, v115, v213
	v_add_f32_e32 v212, v116, v212
	v_add_f32_e32 v213, v117, v213
	v_add_f32_e32 v212, v118, v212
	v_add_f32_e32 v213, v119, v213
	v_add_f32_e32 v212, v120, v212
	v_add_f32_e32 v213, v121, v213
	v_add_f32_e32 v212, v122, v212
	v_add_f32_e32 v213, v123, v213
	v_add_f32_e32 v212, v124, v212
	v_add_f32_e32 v213, v125, v213
	v_add_f32_e32 v212, v126, v212
	v_add_f32_e32 v213, v127, v213
	v_add_f32_e32 v212, v128, v212
	v_add_f32_e32 v213, v129, v213
	v_add_f32_e32 v212, v212, v213
	v_fma_f32 v255, v255, v215, v212
	v_cvt_pk_bf16_f32 v98, v98, v99
	v_cvt_pk_bf16_f32 v99, v100, v101
	v_cvt_pk_bf16_f32 v100, v102, v103
	v_cvt_pk_bf16_f32 v101, v104, v105
	v_cvt_pk_bf16_f32 v102, v106, v107
	v_cvt_pk_bf16_f32 v103, v108, v109
	v_cvt_pk_bf16_f32 v104, v110, v111
	v_cvt_pk_bf16_f32 v105, v112, v113
	v_cvt_pk_bf16_f32 v114, v114, v115
	v_cvt_pk_bf16_f32 v115, v116, v117
	v_cvt_pk_bf16_f32 v116, v118, v119
	v_cvt_pk_bf16_f32 v117, v120, v121
	v_cvt_pk_bf16_f32 v118, v122, v123
	v_cvt_pk_bf16_f32 v119, v124, v125
	v_cvt_pk_bf16_f32 v120, v126, v127
	v_cvt_pk_bf16_f32 v121, v128, v129
	v_permlane32_swap_b32_e32 v98, v100
	v_permlane32_swap_b32_e32 v99, v101
	v_permlane32_swap_b32_e32 v102, v104
	v_permlane32_swap_b32_e32 v103, v105
	v_permlane32_swap_b32_e32 v114, v116
	v_permlane32_swap_b32_e32 v115, v117
	v_permlane32_swap_b32_e32 v118, v120
	v_permlane32_swap_b32_e32 v119, v121
	v_cmp_gt_f32_e32 vcc, 1.0, v215
	s_cbranch_vccz .LA_rs1
	s_and_saveexec_b64 s[60:61], s[4:5]
	ds_write_b32 v234, v215 offset:128
	s_or_b64 exec, exec, s[60:61]
	s_waitcnt lgkmcnt(0)
	v_add_u32_e32 v245, v232, v233
	ds_read_b128 v[220:223], v245 offset:224
	ds_read_b128 v[224:227], v245 offset:192
	ds_read_b128 v[216:219], v245 offset:160
	ds_read_b128 v[212:215], v245 offset:128
	s_waitcnt lgkmcnt(0)
	v_mul_f32_e32 v44, v44, v220
	v_mul_f32_e32 v45, v45, v221
	v_mul_f32_e32 v46, v46, v222
	v_mul_f32_e32 v47, v47, v223
	v_mul_f32_e32 v40, v40, v224
	v_mul_f32_e32 v41, v41, v225
	v_mul_f32_e32 v42, v42, v226
	v_mul_f32_e32 v43, v43, v227
	v_mul_f32_e32 v36, v36, v216
	v_mul_f32_e32 v37, v37, v217
	v_mul_f32_e32 v38, v38, v218
	v_mul_f32_e32 v39, v39, v219
	v_mul_f32_e32 v32, v32, v212
	v_mul_f32_e32 v33, v33, v213
	v_mul_f32_e32 v34, v34, v214
	v_mul_f32_e32 v35, v35, v215
	v_mul_f32_e32 v60, v60, v220
	v_mul_f32_e32 v61, v61, v221
	v_mul_f32_e32 v62, v62, v222
	v_mul_f32_e32 v63, v63, v223
	v_mul_f32_e32 v56, v56, v224
	v_mul_f32_e32 v57, v57, v225
	v_mul_f32_e32 v58, v58, v226
	v_mul_f32_e32 v59, v59, v227
	v_mul_f32_e32 v52, v52, v216
	v_mul_f32_e32 v53, v53, v217
	v_mul_f32_e32 v54, v54, v218
	v_mul_f32_e32 v55, v55, v219
	v_mul_f32_e32 v48, v48, v212
	v_mul_f32_e32 v49, v49, v213
	v_mul_f32_e32 v50, v50, v214
	v_mul_f32_e32 v51, v51, v215
; __device__ __forceinline__ unsigned f2bf(float f) { unsigned u = __builtin_bit_cast(unsigned, f); return (u + 0x7fffu + ((u >> 16) & 1u)) >> 16; }
; #define SBAR() __builtin_amdgcn_sched_barrier(0)
; __device__ __forceinline__ int crow(int r, int hi) { return (r & 3) + 8 * (r >> 2) + 4 * hi; }
; template <int D0> __device__ __forceinline__ void pv_one(f32x16& od, int vb, bf16x8 pa0, bf16x8 pa1, bf16x8 pa2, bf16x8 pa3) {
;     const s16x4 l0 = tr_read<v_rd_off(D0, 0, 0)>(vb), h0 = tr_read<v_rd_off(D0, 0, 1)>(vb), l1 = tr_read<v_rd_off(D0, 1, 0)>(vb), h1 = tr_read<v_rd_off(D0, 1, 1)>(vb);
;     const s16x4 l2 = tr_read<v_rd_off(D0, 2, 0)>(vb), h2 = tr_read<v_rd_off(D0, 2, 1)>(vb), l3 = tr_read<v_rd_off(D0, 3, 0)>(vb), h3 = tr_read<v_rd_off(D0, 3, 1)>(vb);
;     asm volatile("s_waitcnt lgkmcnt(0)" ::: "memory"); SBAR();
;     ...
;     od = __builtin_amdgcn_mfma_f32_32x32x16_bf16(pa0, PK(l0, h0), od, 0, 0, 0);
;     od = __builtin_amdgcn_mfma_f32_32x32x16_bf16(pa1, PK(l1, h1), od, 0, 0, 0);
;     od = __builtin_amdgcn_mfma_f32_32x32x16_bf16(pa2, PK(l2, h2), od, 0, 0, 0);
;     od = __builtin_amdgcn_mfma_f32_32x32x16_bf16(pa3, PK(l3, h3), od, 0, 0, 0);
;     ...
; }
; __device__ __forceinline__ void attn_body(const bf16_t* __restrict__ Qb, const bf16_t* __restrict__ KVh, const bf16_t* __restrict__ KR, const float* __restrict__ ropeq,
;                                           bf16_t* __restrict__ Ob, int seq, char* lds, const int tid) {
;     ...
;     if (hi == 0) li_l[r32] = l_reg; asm volatile("s_waitcnt lgkmcnt(0)" ::: "memory");
;     float rli[16];
; #pragma unroll
;     for (int r = 0; r < 16; ++r) rli[r] = __builtin_amdgcn_rcpf(li_l[crow(r, hi)]);
;     bf16_t* Ow = Ob + (size_t)(wid * QBLK) * DM;
; #pragma unroll
;     for (int r = 0; r < 16; ++r) { const int orow = crow(r, hi);
; #pragma unroll
;         for (int d0 = 0; d0 < 2; ++d0) Ow[(size_t)orow * DM + d0 * 32 + r32] = (bf16_t)f2bf(o[d0][r] * rli[r]); }
.LA_rs1:
	v_add_u32_e32 v247, s18, v235
	ds_read_b64_tr_b16 v[74:75], v247 offset:0
	ds_read_b64_tr_b16 v[76:77], v247 offset:2048
	ds_read_b64_tr_b16 v[78:79], v247 offset:4096
	ds_read_b64_tr_b16 v[80:81], v247 offset:6144
	ds_read_b64_tr_b16 v[90:91], v247 offset:8192
	ds_read_b64_tr_b16 v[92:93], v247 offset:10240
	ds_read_b64_tr_b16 v[94:95], v247 offset:12288
	ds_read_b64_tr_b16 v[96:97], v247 offset:14336
	ds_read_b64_tr_b16 v[106:107], v247 offset:512
	ds_read_b64_tr_b16 v[108:109], v247 offset:2560
	ds_read_b64_tr_b16 v[110:111], v247 offset:4608
	ds_read_b64_tr_b16 v[112:113], v247 offset:6656
	ds_read_b64_tr_b16 v[122:123], v247 offset:8704
	ds_read_b64_tr_b16 v[124:125], v247 offset:10752
	ds_read_b64_tr_b16 v[126:127], v247 offset:12800
	ds_read_b64_tr_b16 v[128:129], v247 offset:14848
	s_waitcnt lgkmcnt(14)
	v_mfma_f32_32x32x16_bf16 v[0:15], v[66:69], v[74:77], v[0:15]
	v_mfma_f32_32x32x16_bf16 v[32:47], v[98:101], v[74:77], v[32:47]
	s_waitcnt lgkmcnt(12)
	v_mfma_f32_32x32x16_bf16 v[0:15], v[70:73], v[78:81], v[0:15]
	v_mfma_f32_32x32x16_bf16 v[32:47], v[102:105], v[78:81], v[32:47]
	s_waitcnt lgkmcnt(10)
	v_mfma_f32_32x32x16_bf16 v[0:15], v[82:85], v[90:93], v[0:15]
	v_mfma_f32_32x32x16_bf16 v[32:47], v[114:117], v[90:93], v[32:47]
	s_waitcnt lgkmcnt(8)
	v_mfma_f32_32x32x16_bf16 v[0:15], v[86:89], v[94:97], v[0:15]
	v_mfma_f32_32x32x16_bf16 v[32:47], v[118:121], v[94:97], v[32:47]
	s_waitcnt lgkmcnt(6)
	v_mfma_f32_32x32x16_bf16 v[16:31], v[66:69], v[106:109], v[16:31]
	v_mfma_f32_32x32x16_bf16 v[48:63], v[98:101], v[106:109], v[48:63]
	s_waitcnt lgkmcnt(4)
	v_mfma_f32_32x32x16_bf16 v[16:31], v[70:73], v[110:113], v[16:31]
	v_mfma_f32_32x32x16_bf16 v[48:63], v[102:105], v[110:113], v[48:63]
	s_waitcnt lgkmcnt(2)
	v_mfma_f32_32x32x16_bf16 v[16:31], v[82:85], v[122:125], v[16:31]
	v_mfma_f32_32x32x16_bf16 v[48:63], v[114:117], v[122:125], v[48:63]
	s_waitcnt lgkmcnt(0)
	v_mfma_f32_32x32x16_bf16 v[16:31], v[86:89], v[126:129], v[16:31]
	v_mfma_f32_32x32x16_bf16 v[48:63], v[118:121], v[126:129], v[48:63]
	s_waitcnt lgkmcnt(0)
	s_barrier
	s_add_i32 s16, s16, 1
	s_mov_b32 s17, s18
	s_mov_b32 s18, s19
	s_mov_b32 s19, s22
	s_mov_b32 s22, s17
	s_cmp_lt_u32 s16, 64
	s_cbranch_scc1 .LA_loop
	v_and_b32_e32 v245, 31, v211
	v_lshrrev_b32_e32 v246, 5, v211
	v_lshlrev_b32_e32 v202, 1, v245
	v_lshl_add_u32 v202, v246, 13, v202
	v_mov_b32_e32 v203, v254
	s_nop 1
	v_permlane32_swap_b32_e32 v254, v203
	v_add_f32_e32 v254, v254, v203
	s_and_saveexec_b64 s[60:61], s[4:5]
	ds_write_b32 v234, v254
	s_or_b64 exec, exec, s[60:61]
	s_waitcnt lgkmcnt(0)
	v_add_u32_e32 v245, v232, v233
	ds_read_b128 v[212:215], v245 offset:0
	ds_read_b128 v[216:219], v245 offset:32
	ds_read_b128 v[220:223], v245 offset:64
	ds_read_b128 v[224:227], v245 offset:96
	s_waitcnt lgkmcnt(0)
	v_rcp_f32_e32 v212, v212
	v_rcp_f32_e32 v213, v213
	v_rcp_f32_e32 v214, v214
	v_rcp_f32_e32 v215, v215
	v_rcp_f32_e32 v216, v216
	v_rcp_f32_e32 v217, v217
	v_rcp_f32_e32 v218, v218
	v_rcp_f32_e32 v219, v219
	v_rcp_f32_e32 v220, v220
	v_rcp_f32_e32 v221, v221
	v_rcp_f32_e32 v222, v222
	v_rcp_f32_e32 v223, v223
	v_rcp_f32_e32 v224, v224
	v_rcp_f32_e32 v225, v225
	v_rcp_f32_e32 v226, v226
	v_rcp_f32_e32 v227, v227
	v_add_u32_e32 v246, 0x0, v202
	v_mul_f32_e32 v0, v0, v212
	v_bfe_u32 v247, v0, 16, 1
	v_add3_u32 v0, v0, v247, s33
	global_store_short_d16_hi v246, v0, s[42:43] offset:0
	v_mul_f32_e32 v16, v16, v212
	v_bfe_u32 v247, v16, 16, 1
	v_add3_u32 v16, v16, v247, s33
	global_store_short_d16_hi v246, v16, s[42:43] offset:64
	v_mul_f32_e32 v1, v1, v213
	v_bfe_u32 v247, v1, 16, 1
	v_add3_u32 v1, v1, v247, s33
	global_store_short_d16_hi v246, v1, s[42:43] offset:2048
	v_mul_f32_e32 v17, v17, v213
	v_bfe_u32 v247, v17, 16, 1
	v_add3_u32 v17, v17, v247, s33
	global_store_short_d16_hi v246, v17, s[42:43] offset:2112
	v_add_u32_e32 v246, 0x1000, v202
	v_mul_f32_e32 v2, v2, v214
	v_bfe_u32 v247, v2, 16, 1
	v_add3_u32 v2, v2, v247, s33
	global_store_short_d16_hi v246, v2, s[42:43] offset:0
	v_mul_f32_e32 v18, v18, v214
	v_bfe_u32 v247, v18, 16, 1
	v_add3_u32 v18, v18, v247, s33
	global_store_short_d16_hi v246, v18, s[42:43] offset:64
	v_mul_f32_e32 v3, v3, v215
	v_bfe_u32 v247, v3, 16, 1
	v_add3_u32 v3, v3, v247, s33
	global_store_short_d16_hi v246, v3, s[42:43] offset:2048
	v_mul_f32_e32 v19, v19, v215
	v_bfe_u32 v247, v19, 16, 1
	v_add3_u32 v19, v19, v247, s33
	global_store_short_d16_hi v246, v19, s[42:43] offset:2112
	v_add_u32_e32 v246, 0x4000, v202
	v_mul_f32_e32 v4, v4, v216
	v_bfe_u32 v247, v4, 16, 1
	v_add3_u32 v4, v4, v247, s33
	global_store_short_d16_hi v246, v4, s[42:43] offset:0
	v_mul_f32_e32 v20, v20, v216
	v_bfe_u32 v247, v20, 16, 1
	v_add3_u32 v20, v20, v247, s33
	global_store_short_d16_hi v246, v20, s[42:43] offset:64
	v_mul_f32_e32 v5, v5, v217
	v_bfe_u32 v247, v5, 16, 1
	v_add3_u32 v5, v5, v247, s33
	global_store_short_d16_hi v246, v5, s[42:43] offset:2048
	v_mul_f32_e32 v21, v21, v217
	v_bfe_u32 v247, v21, 16, 1
	v_add3_u32 v21, v21, v247, s33
	global_store_short_d16_hi v246, v21, s[42:43] offset:2112
	v_add_u32_e32 v246, 0x5000, v202
	v_mul_f32_e32 v6, v6, v218
	v_bfe_u32 v247, v6, 16, 1
	v_add3_u32 v6, v6, v247, s33
	global_store_short_d16_hi v246, v6, s[42:43] offset:0
	v_mul_f32_e32 v22, v22, v218
	v_bfe_u32 v247, v22, 16, 1
	v_add3_u32 v22, v22, v247, s33
	global_store_short_d16_hi v246, v22, s[42:43] offset:64
	v_mul_f32_e32 v7, v7, v219
	v_bfe_u32 v247, v7, 16, 1
	v_add3_u32 v7, v7, v247, s33
	global_store_short_d16_hi v246, v7, s[42:43] offset:2048
	v_mul_f32_e32 v23, v23, v219
	v_bfe_u32 v247, v23, 16, 1
	v_add3_u32 v23, v23, v247, s33
	global_store_short_d16_hi v246, v23, s[42:43] offset:2112
; __device__ __forceinline__ unsigned f2bf(float f) { unsigned u = __builtin_bit_cast(unsigned, f); return (u + 0x7fffu + ((u >> 16) & 1u)) >> 16; }
; __device__ __forceinline__ int crow(int r, int hi) { return (r & 3) + 8 * (r >> 2) + 4 * hi; }
; __device__ __forceinline__ void attn_body(const bf16_t* __restrict__ Qb, const bf16_t* __restrict__ KVh, const bf16_t* __restrict__ KR, const float* __restrict__ ropeq,
;                                           bf16_t* __restrict__ Ob, int seq, char* lds, const int tid) {
;     ...
;     if (hi == 0) li_l[r32] = l_reg; asm volatile("s_waitcnt lgkmcnt(0)" ::: "memory");
;     float rli[16];
; #pragma unroll
;     for (int r = 0; r < 16; ++r) rli[r] = __builtin_amdgcn_rcpf(li_l[crow(r, hi)]);
;     bf16_t* Ow = Ob + (size_t)(wid * QBLK) * DM;
; #pragma unroll
;     for (int r = 0; r < 16; ++r) { const int orow = crow(r, hi);
; #pragma unroll
;         for (int d0 = 0; d0 < 2; ++d0) Ow[(size_t)orow * DM + d0 * 32 + r32] = (bf16_t)f2bf(o[d0][r] * rli[r]); }
	v_add_u32_e32 v246, 0x8000, v202
	v_mul_f32_e32 v8, v8, v220
	v_bfe_u32 v247, v8, 16, 1
	v_add3_u32 v8, v8, v247, s33
	global_store_short_d16_hi v246, v8, s[42:43] offset:0
	v_mul_f32_e32 v24, v24, v220
	v_bfe_u32 v247, v24, 16, 1
	v_add3_u32 v24, v24, v247, s33
	global_store_short_d16_hi v246, v24, s[42:43] offset:64
	v_mul_f32_e32 v9, v9, v221
	v_bfe_u32 v247, v9, 16, 1
	v_add3_u32 v9, v9, v247, s33
	global_store_short_d16_hi v246, v9, s[42:43] offset:2048
	v_mul_f32_e32 v25, v25, v221
	v_bfe_u32 v247, v25, 16, 1
	v_add3_u32 v25, v25, v247, s33
	global_store_short_d16_hi v246, v25, s[42:43] offset:2112
	v_add_u32_e32 v246, 0x9000, v202
	v_mul_f32_e32 v10, v10, v222
	v_bfe_u32 v247, v10, 16, 1
	v_add3_u32 v10, v10, v247, s33
	global_store_short_d16_hi v246, v10, s[42:43] offset:0
	v_mul_f32_e32 v26, v26, v222
	v_bfe_u32 v247, v26, 16, 1
	v_add3_u32 v26, v26, v247, s33
	global_store_short_d16_hi v246, v26, s[42:43] offset:64
	v_mul_f32_e32 v11, v11, v223
	v_bfe_u32 v247, v11, 16, 1
	v_add3_u32 v11, v11, v247, s33
	global_store_short_d16_hi v246, v11, s[42:43] offset:2048
	v_mul_f32_e32 v27, v27, v223
	v_bfe_u32 v247, v27, 16, 1
	v_add3_u32 v27, v27, v247, s33
	global_store_short_d16_hi v246, v27, s[42:43] offset:2112
	v_add_u32_e32 v246, 0xc000, v202
	v_mul_f32_e32 v12, v12, v224
	v_bfe_u32 v247, v12, 16, 1
	v_add3_u32 v12, v12, v247, s33
	global_store_short_d16_hi v246, v12, s[42:43] offset:0
	v_mul_f32_e32 v28, v28, v224
	v_bfe_u32 v247, v28, 16, 1
	v_add3_u32 v28, v28, v247, s33
	global_store_short_d16_hi v246, v28, s[42:43] offset:64
	v_mul_f32_e32 v13, v13, v225
	v_bfe_u32 v247, v13, 16, 1
	v_add3_u32 v13, v13, v247, s33
	global_store_short_d16_hi v246, v13, s[42:43] offset:2048
	v_mul_f32_e32 v29, v29, v225
	v_bfe_u32 v247, v29, 16, 1
	v_add3_u32 v29, v29, v247, s33
	global_store_short_d16_hi v246, v29, s[42:43] offset:2112
	v_add_u32_e32 v246, 0xd000, v202
	v_mul_f32_e32 v14, v14, v226
	v_bfe_u32 v247, v14, 16, 1
	v_add3_u32 v14, v14, v247, s33
	global_store_short_d16_hi v246, v14, s[42:43] offset:0
	v_mul_f32_e32 v30, v30, v226
	v_bfe_u32 v247, v30, 16, 1
	v_add3_u32 v30, v30, v247, s33
	global_store_short_d16_hi v246, v30, s[42:43] offset:64
	v_mul_f32_e32 v15, v15, v227
	v_bfe_u32 v247, v15, 16, 1
	v_add3_u32 v15, v15, v247, s33
	global_store_short_d16_hi v246, v15, s[42:43] offset:2048
	v_mul_f32_e32 v31, v31, v227
	v_bfe_u32 v247, v31, 16, 1
	v_add3_u32 v31, v31, v247, s33
	global_store_short_d16_hi v246, v31, s[42:43] offset:2112
	s_waitcnt lgkmcnt(0)
	v_mov_b32_e32 v203, v255
	s_nop 1
	v_permlane32_swap_b32_e32 v255, v203
	v_add_f32_e32 v255, v255, v203
	s_and_saveexec_b64 s[60:61], s[4:5]
	ds_write_b32 v234, v255
	s_or_b64 exec, exec, s[60:61]
	s_waitcnt lgkmcnt(0)
	v_add_u32_e32 v245, v232, v233
	ds_read_b128 v[212:215], v245 offset:0
	ds_read_b128 v[216:219], v245 offset:32
	ds_read_b128 v[220:223], v245 offset:64
	ds_read_b128 v[224:227], v245 offset:96
	s_waitcnt lgkmcnt(0)
; __device__ __forceinline__ unsigned f2bf(float f) { unsigned u = __builtin_bit_cast(unsigned, f); return (u + 0x7fffu + ((u >> 16) & 1u)) >> 16; }
; __device__ __forceinline__ int crow(int r, int hi) { return (r & 3) + 8 * (r >> 2) + 4 * hi; }
; __device__ __forceinline__ void attn_body(const bf16_t* __restrict__ Qb, const bf16_t* __restrict__ KVh, const bf16_t* __restrict__ KR, const float* __restrict__ ropeq,
;                                           bf16_t* __restrict__ Ob, int seq, char* lds, const int tid) {
;     ...
;     if (hi == 0) li_l[r32] = l_reg; asm volatile("s_waitcnt lgkmcnt(0)" ::: "memory");
;     float rli[16];
; #pragma unroll
;     for (int r = 0; r < 16; ++r) rli[r] = __builtin_amdgcn_rcpf(li_l[crow(r, hi)]);
;     bf16_t* Ow = Ob + (size_t)(wid * QBLK) * DM;
; #pragma unroll
;     for (int r = 0; r < 16; ++r) { const int orow = crow(r, hi);
; #pragma unroll
;         for (int d0 = 0; d0 < 2; ++d0) Ow[(size_t)orow * DM + d0 * 32 + r32] = (bf16_t)f2bf(o[d0][r] * rli[r]); }
; __device__ __forceinline__ void phase_attn(const Ctx& C, PP p, char* lds_generic) {
;     ...
;     for (int it = C.vcu; it < 2048; it += C.G) {
;         const int qb = it & 15, h = (it >> 4) & 15, b = it >> 8; const size_t t0 = (size_t)b * SEQ, q0 = t0 + qb * 256;
;         __syncthreads();
;         att::attn_body(Q + q0 * NQ + h * 96, KV + t0 * NKV + h * 128, KR + t0 * 32, rope + q0 * 32, O + q0 * DM + h * 64, SEQ, lds_generic, C.tid);
;     }
	v_rcp_f32_e32 v212, v212
	v_rcp_f32_e32 v213, v213
	v_rcp_f32_e32 v214, v214
	v_rcp_f32_e32 v215, v215
	v_rcp_f32_e32 v216, v216
	v_rcp_f32_e32 v217, v217
	v_rcp_f32_e32 v218, v218
	v_rcp_f32_e32 v219, v219
	v_rcp_f32_e32 v220, v220
	v_rcp_f32_e32 v221, v221
	v_rcp_f32_e32 v222, v222
	v_rcp_f32_e32 v223, v223
	v_rcp_f32_e32 v224, v224
	v_rcp_f32_e32 v225, v225
	v_rcp_f32_e32 v226, v226
	v_rcp_f32_e32 v227, v227
	v_add_u32_e32 v246, 0x10000, v202
	v_mul_f32_e32 v32, v32, v212
	v_bfe_u32 v247, v32, 16, 1
	v_add3_u32 v32, v32, v247, s33
	global_store_short_d16_hi v246, v32, s[42:43] offset:0
	v_mul_f32_e32 v48, v48, v212
	v_bfe_u32 v247, v48, 16, 1
	v_add3_u32 v48, v48, v247, s33
	global_store_short_d16_hi v246, v48, s[42:43] offset:64
	v_mul_f32_e32 v33, v33, v213
	v_bfe_u32 v247, v33, 16, 1
	v_add3_u32 v33, v33, v247, s33
	global_store_short_d16_hi v246, v33, s[42:43] offset:2048
	v_mul_f32_e32 v49, v49, v213
	v_bfe_u32 v247, v49, 16, 1
	v_add3_u32 v49, v49, v247, s33
	global_store_short_d16_hi v246, v49, s[42:43] offset:2112
	v_add_u32_e32 v246, 0x11000, v202
	v_mul_f32_e32 v34, v34, v214
	v_bfe_u32 v247, v34, 16, 1
	v_add3_u32 v34, v34, v247, s33
	global_store_short_d16_hi v246, v34, s[42:43] offset:0
	v_mul_f32_e32 v50, v50, v214
	v_bfe_u32 v247, v50, 16, 1
	v_add3_u32 v50, v50, v247, s33
	global_store_short_d16_hi v246, v50, s[42:43] offset:64
	v_mul_f32_e32 v35, v35, v215
	v_bfe_u32 v247, v35, 16, 1
	v_add3_u32 v35, v35, v247, s33
	global_store_short_d16_hi v246, v35, s[42:43] offset:2048
	v_mul_f32_e32 v51, v51, v215
	v_bfe_u32 v247, v51, 16, 1
	v_add3_u32 v51, v51, v247, s33
	global_store_short_d16_hi v246, v51, s[42:43] offset:2112
	v_add_u32_e32 v246, 0x14000, v202
	v_mul_f32_e32 v36, v36, v216
	v_bfe_u32 v247, v36, 16, 1
	v_add3_u32 v36, v36, v247, s33
	global_store_short_d16_hi v246, v36, s[42:43] offset:0
	v_mul_f32_e32 v52, v52, v216
	v_bfe_u32 v247, v52, 16, 1
	v_add3_u32 v52, v52, v247, s33
	global_store_short_d16_hi v246, v52, s[42:43] offset:64
	v_mul_f32_e32 v37, v37, v217
	v_bfe_u32 v247, v37, 16, 1
	v_add3_u32 v37, v37, v247, s33
	global_store_short_d16_hi v246, v37, s[42:43] offset:2048
	v_mul_f32_e32 v53, v53, v217
	v_bfe_u32 v247, v53, 16, 1
	v_add3_u32 v53, v53, v247, s33
	global_store_short_d16_hi v246, v53, s[42:43] offset:2112
	v_add_u32_e32 v246, 0x15000, v202
	v_mul_f32_e32 v38, v38, v218
	v_bfe_u32 v247, v38, 16, 1
	v_add3_u32 v38, v38, v247, s33
	global_store_short_d16_hi v246, v38, s[42:43] offset:0
	v_mul_f32_e32 v54, v54, v218
	v_bfe_u32 v247, v54, 16, 1
	v_add3_u32 v54, v54, v247, s33
	global_store_short_d16_hi v246, v54, s[42:43] offset:64
	v_mul_f32_e32 v39, v39, v219
	v_bfe_u32 v247, v39, 16, 1
	v_add3_u32 v39, v39, v247, s33
	global_store_short_d16_hi v246, v39, s[42:43] offset:2048
	v_mul_f32_e32 v55, v55, v219
	v_bfe_u32 v247, v55, 16, 1
	v_add3_u32 v55, v55, v247, s33
	global_store_short_d16_hi v246, v55, s[42:43] offset:2112
	v_add_u32_e32 v246, 0x18000, v202
	v_mul_f32_e32 v40, v40, v220
	v_bfe_u32 v247, v40, 16, 1
	v_add3_u32 v40, v40, v247, s33
	global_store_short_d16_hi v246, v40, s[42:43] offset:0
	v_mul_f32_e32 v56, v56, v220
	v_bfe_u32 v247, v56, 16, 1
	v_add3_u32 v56, v56, v247, s33
	global_store_short_d16_hi v246, v56, s[42:43] offset:64
	v_mul_f32_e32 v41, v41, v221
	v_bfe_u32 v247, v41, 16, 1
	v_add3_u32 v41, v41, v247, s33
	global_store_short_d16_hi v246, v41, s[42:43] offset:2048
	v_mul_f32_e32 v57, v57, v221
	v_bfe_u32 v247, v57, 16, 1
	v_add3_u32 v57, v57, v247, s33
	global_store_short_d16_hi v246, v57, s[42:43] offset:2112
	v_add_u32_e32 v246, 0x19000, v202
	v_mul_f32_e32 v42, v42, v222
	v_bfe_u32 v247, v42, 16, 1
	v_add3_u32 v42, v42, v247, s33
	global_store_short_d16_hi v246, v42, s[42:43] offset:0
	v_mul_f32_e32 v58, v58, v222
	v_bfe_u32 v247, v58, 16, 1
	v_add3_u32 v58, v58, v247, s33
	global_store_short_d16_hi v246, v58, s[42:43] offset:64
	v_mul_f32_e32 v43, v43, v223
	v_bfe_u32 v247, v43, 16, 1
	v_add3_u32 v43, v43, v247, s33
	global_store_short_d16_hi v246, v43, s[42:43] offset:2048
	v_mul_f32_e32 v59, v59, v223
	v_bfe_u32 v247, v59, 16, 1
	v_add3_u32 v59, v59, v247, s33
	global_store_short_d16_hi v246, v59, s[42:43] offset:2112
	v_add_u32_e32 v246, 0x1c000, v202
	v_mul_f32_e32 v44, v44, v224
	v_bfe_u32 v247, v44, 16, 1
	v_add3_u32 v44, v44, v247, s33
	global_store_short_d16_hi v246, v44, s[42:43] offset:0
	v_mul_f32_e32 v60, v60, v224
	v_bfe_u32 v247, v60, 16, 1
	v_add3_u32 v60, v60, v247, s33
	global_store_short_d16_hi v246, v60, s[42:43] offset:64
	v_mul_f32_e32 v45, v45, v225
	v_bfe_u32 v247, v45, 16, 1
	v_add3_u32 v45, v45, v247, s33
	global_store_short_d16_hi v246, v45, s[42:43] offset:2048
	v_mul_f32_e32 v61, v61, v225
	v_bfe_u32 v247, v61, 16, 1
	v_add3_u32 v61, v61, v247, s33
	global_store_short_d16_hi v246, v61, s[42:43] offset:2112
	v_add_u32_e32 v246, 0x1d000, v202
	v_mul_f32_e32 v46, v46, v226
	v_bfe_u32 v247, v46, 16, 1
	v_add3_u32 v46, v46, v247, s33
	global_store_short_d16_hi v246, v46, s[42:43] offset:0
	v_mul_f32_e32 v62, v62, v226
	v_bfe_u32 v247, v62, 16, 1
	v_add3_u32 v62, v62, v247, s33
	global_store_short_d16_hi v246, v62, s[42:43] offset:64
	v_mul_f32_e32 v47, v47, v227
	v_bfe_u32 v247, v47, 16, 1
	v_add3_u32 v47, v47, v247, s33
	global_store_short_d16_hi v246, v47, s[42:43] offset:2048
	v_mul_f32_e32 v63, v63, v227
	v_bfe_u32 v247, v63, 16, 1
	v_add3_u32 v63, v63, v247, s33
	global_store_short_d16_hi v246, v63, s[42:43] offset:2112
	s_waitcnt lgkmcnt(0)
	s_add_i32 s20, s20, s85
	s_cmpk_lt_i32 s20, 0x400
	s_cbranch_scc1 .LA_item
	s_branch .LBB0_78
